# differential-attention lambda computed once for all four layers in the kernel prologue (parked in v255 lanes) instead of four loads plus two wave reductions at every attention phase entry
# speedup vs baseline: 1.0056x; 1.0056x over previous
.LBB0_5:
	s_or_b64 exec, exec, s[4:5]
	v_readlane_b32 s4, v253, 1
	v_readlane_b32 s5, v253, 2
	s_load_dwordx2 s[30:31], s[4:5], 0x110
	s_waitcnt lgkmcnt(0)
	s_cmp_ge_i32 s30, s31
	s_cbranch_scc1 .LBB0_833
	s_cmpk_gt_i32 s31, 0x1000
	v_lshrrev_b32_e32 v1, 20, v0
	v_lshrrev_b32_e32 v0, 10, v0
	s_cselect_b64 s[6:7], -1, 0
	v_or_b32_e32 v0, v0, v1
	s_movk_i32 s5, 0x3ff
	v_writelane_b32 v253, s6, 7
	v_and_or_b32 v0, v0, s5, v202
	s_mov_b64 s[16:17], s[64:65]
	v_writelane_b32 v253, s7, 8
	v_cmp_eq_u32_e64 s[6:7], 0, v0
	s_mul_i32 s4, s17, s16
	v_mbcnt_lo_u32_b32 v0, -1, 0
	v_writelane_b32 v253, s6, 9
	v_mbcnt_hi_u32_b32 v207, -1, v0
	v_and_b32_e32 v0, 64, v207
	v_writelane_b32 v253, s7, 10
	s_movk_i32 s75, 0x1000
	v_readlane_b32 s10, v253, 1
	v_readlane_b32 s11, v253, 2
	s_load_dword s5, s[10:11], 0x120
	s_mov_b32 s9, 0
	v_mov_b32_e32 v1, 0
	v_mov_b32_e32 v203, 0x22000
	v_mov_b32_e32 v204, 0x22004
	s_waitcnt lgkmcnt(0)
	s_mul_i32 s68, s4, s5
	s_add_u32 s4, s0, 0x16ab8200
	s_addc_u32 s5, s1, 0
	s_add_u32 s80, s0, 0x16ab8400
	v_writelane_b32 v253, s4, 11
	s_addc_u32 s81, s1, 0
	v_mov_b32_e32 v205, 0x358637bd
	v_writelane_b32 v253, s5, 12
	s_add_u32 s4, s0, 0x16ab8500
	s_addc_u32 s5, s1, 0
	v_writelane_b32 v253, s4, 13
	s_mov_b32 s33, 0x800000
	s_movk_i32 s82, 0x6000
	v_writelane_b32 v253, s5, 14
	s_add_u32 s4, s0, 0x16ab8600
	s_addc_u32 s5, s1, 0
	v_writelane_b32 v253, s4, 15
	s_mov_b64 s[96:97], 0xc0
	s_mov_b64 s[72:73], 0x100
	v_writelane_b32 v253, s5, 16
	s_add_u32 s4, s0, 0x16ab8700
	s_addc_u32 s5, s1, 0
	v_writelane_b32 v253, s4, 17
	s_movk_i32 s83, 0x110
	s_mov_b64 s[76:77], 0x4000
	v_writelane_b32 v253, s5, 18
	s_add_u32 s4, s0, 0x16ab8800
	s_addc_u32 s5, s1, 0
	v_writelane_b32 v253, s4, 19
	s_movk_i32 s84, 0xc00
	s_mov_b32 s74, 0x3fb8aa3b
	v_writelane_b32 v253, s5, 20
	s_add_u32 s4, s0, 0x16ab8900
	s_addc_u32 s5, s1, 0
	v_writelane_b32 v253, s4, 21
	v_mov_b32_e32 v206, 0x22010
	s_movk_i32 s85, 0xfefe
	v_writelane_b32 v253, s5, 22
	s_add_u32 s4, s0, 0x16ab8a00
	s_addc_u32 s5, s1, 0
	v_writelane_b32 v253, s4, 23
	v_add_u32_e32 v208, 64, v0
	v_xor_b32_e32 v209, 32, v207
	v_writelane_b32 v253, s5, 24
	s_add_u32 s4, s0, 0x16ab8b00
	s_addc_u32 s5, s1, 0
	v_writelane_b32 v253, s4, 25
	v_xor_b32_e32 v210, 16, v207
	v_xor_b32_e32 v211, 8, v207
	v_writelane_b32 v253, s5, 26
	s_add_u32 s4, s0, 0x16ab8c00
	s_addc_u32 s5, s1, 0
	v_writelane_b32 v253, s4, 27
	v_xor_b32_e32 v212, 4, v207
	v_xor_b32_e32 v213, 2, v207
	v_writelane_b32 v253, s5, 28
	s_add_u32 s4, s0, 0x16ab8d00
	s_addc_u32 s5, s1, 0
	v_writelane_b32 v253, s4, 29
	v_xor_b32_e32 v214, 1, v207
	v_mov_b32_e32 v215, 0xf149f2ca
	v_writelane_b32 v253, s5, 30
	s_add_u32 s4, s0, 0x16ab8e00
	s_addc_u32 s5, s1, 0
	v_writelane_b32 v253, s4, 31
	v_mov_b32_e32 v216, 0x1000000
	v_mov_b32_e32 v217, 0xa8
	v_writelane_b32 v253, s5, 32
	s_add_u32 s4, s0, 0x16ab8f00
	s_addc_u32 s5, s1, 0
	v_writelane_b32 v253, s4, 33
	v_mov_b32_e32 v218, 0xa0
	v_mov_b32_e32 v219, 0x80
	v_writelane_b32 v253, s5, 34
	s_add_u32 s4, s0, 0x16ab9000
	s_addc_u32 s5, s1, 0
	v_writelane_b32 v253, s4, 35
	v_mov_b32_e32 v220, 0x1c00000
	v_mov_b32_e32 v221, 0x1800000
	v_writelane_b32 v253, s5, 36
	s_add_u32 s4, s0, 0x16ab9100
	s_addc_u32 s5, s1, 0
	v_writelane_b32 v253, s4, 37
	v_mov_b32_e32 v222, 0x800000
	v_mov_b32_e32 v224, 0xfffff500
	v_writelane_b32 v253, s5, 38
	s_add_u32 s4, s0, 0x16ab9200
	s_addc_u32 s5, s1, 0
	v_writelane_b32 v253, s4, 39
	v_mov_b32_e32 v225, 0xc0
	v_mov_b32_e32 v252, 0x7fffe200
	v_writelane_b32 v253, s5, 40
	s_add_u32 s4, s0, 0x16ab9300
	s_addc_u32 s5, s1, 0
	v_writelane_b32 v253, s4, 41
	s_cmp_eq_u32 s8, 15
	v_mov_b32_e32 v223, 0xc8
	v_writelane_b32 v253, s5, 42
	s_cselect_b64 s[4:5], -1, 0
	v_writelane_b32 v253, s4, 43
	s_cmp_eq_u32 s8, 14
	v_mov_b32_e32 v228, 0xb8
	v_writelane_b32 v253, s5, 44
	s_cselect_b64 s[4:5], -1, 0
	v_writelane_b32 v253, s4, 45
	s_cmp_eq_u32 s8, 13
	v_mov_b32_e32 v229, 0xfffd0000
	v_writelane_b32 v253, s5, 46
	s_cselect_b64 s[4:5], -1, 0
	v_writelane_b32 v253, s4, 47
	s_cmp_eq_u32 s8, 12
	s_nop 0
	v_writelane_b32 v253, s5, 48
	s_cselect_b64 s[4:5], -1, 0
	v_writelane_b32 v253, s4, 49
	s_cmp_eq_u32 s8, 11
	s_nop 0
	v_writelane_b32 v253, s5, 50
	s_cselect_b64 s[4:5], -1, 0
	v_writelane_b32 v253, s4, 51
	s_cmp_eq_u32 s8, 10
	s_nop 0
	v_writelane_b32 v253, s5, 52
	s_cselect_b64 s[4:5], -1, 0
	v_writelane_b32 v253, s4, 53
	s_cmp_eq_u32 s8, 9
	s_nop 0
	v_writelane_b32 v253, s5, 54
	s_cselect_b64 s[4:5], -1, 0
	v_writelane_b32 v253, s4, 55
	s_cmp_eq_u32 s8, 8
	s_nop 0
	v_writelane_b32 v253, s5, 56
	s_cselect_b64 s[4:5], -1, 0
	v_writelane_b32 v253, s4, 57
	s_cmp_eq_u32 s8, 7
	s_nop 0
	v_writelane_b32 v253, s5, 58
	s_cselect_b64 s[4:5], -1, 0
	v_writelane_b32 v253, s4, 59
	s_cmp_eq_u32 s8, 6
	s_nop 0
	v_writelane_b32 v253, s5, 60
	s_cselect_b64 s[4:5], -1, 0
	v_writelane_b32 v253, s4, 61
	s_cmp_eq_u32 s8, 5
	s_nop 0
	v_writelane_b32 v253, s5, 62
	s_cselect_b64 s[4:5], -1, 0
	v_writelane_b32 v253, s4, 63
	s_cmp_eq_u32 s8, 4
	s_nop 0
	v_writelane_b32 v254, s5, 0
	s_cselect_b64 s[4:5], -1, 0
	v_writelane_b32 v254, s4, 1
	s_cmp_eq_u32 s8, 3
	s_nop 0
	v_writelane_b32 v254, s5, 2
	s_cselect_b64 s[4:5], -1, 0
	v_writelane_b32 v254, s4, 3
	s_cmp_eq_u32 s8, 2
	s_nop 0
	v_writelane_b32 v254, s5, 4
	s_cselect_b64 s[4:5], -1, 0
	v_writelane_b32 v254, s4, 5
	s_cmp_eq_u32 s8, 1
	s_nop 0
	v_writelane_b32 v254, s5, 6
	s_cselect_b64 s[4:5], -1, 0
	v_writelane_b32 v254, s4, 7
	s_cmp_eq_u32 s8, 0
	s_nop 0
	v_writelane_b32 v254, s5, 8
	s_cselect_b64 s[4:5], -1, 0
	v_writelane_b32 v254, s4, 9
	s_nop 1
	v_writelane_b32 v254, s5, 10
	s_lshl_b32 s4, s8, 8
	s_add_u32 s2, s2, s4
	s_addc_u32 s3, s3, 0
	s_add_u32 s4, s2, 0x1400
	s_addc_u32 s5, s3, 0
	v_writelane_b32 v254, s4, 11
	s_add_u32 s2, s2, 0x2400
	s_addc_u32 s3, s3, 0
	v_writelane_b32 v254, s5, 12
	v_writelane_b32 v254, s2, 13
	v_readlane_b32 s8, v253, 0
	s_nop 0
	v_writelane_b32 v254, s3, 14
	s_add_u32 s2, s0, 0x16abb400
	s_addc_u32 s3, s1, 0
	v_writelane_b32 v254, s2, 15
	s_add_u32 s0, s0, 0x16abb500
	s_addc_u32 s1, s1, 0
	v_writelane_b32 v254, s3, 16
	v_writelane_b32 v254, s0, 17
	s_lshl_b32 s70, s16, 3
	s_nop 0
	v_writelane_b32 v254, s1, 18
	s_lshl_b32 s0, s8, 3
	v_writelane_b32 v254, s0, 19
	s_load_dwordx4 s[12:15], s[10:11], 0xf0
	s_load_dwordx8 s[0:7], s[10:11], 0xd0
	s_load_dwordx16 s[48:63], s[10:11], 0x40
	s_waitcnt lgkmcnt(0)
	s_add_u32 s66, s14, 0x86b8000
	v_writelane_b32 v254, s0, 20
	s_addc_u32 s67, s15, 0
	s_cmpk_lt_i32 s8, 0xfd0
	v_writelane_b32 v254, s1, 21
	v_writelane_b32 v254, s2, 22
	v_writelane_b32 v254, s3, 23
	v_writelane_b32 v254, s4, 24
	v_writelane_b32 v254, s5, 25
	v_writelane_b32 v254, s6, 26
	v_writelane_b32 v254, s7, 27
	s_cselect_b64 s[0:1], -1, 0
	v_writelane_b32 v254, s0, 28
	s_nop 1
	v_writelane_b32 v254, s1, 29
	s_add_u32 s0, s14, 0x116b8000
	s_addc_u32 s1, s15, 0
	v_writelane_b32 v254, s0, 30
	s_add_u32 s78, s14, 0x8678000
	s_addc_u32 s79, s15, 0
	v_writelane_b32 v254, s1, 31
	s_load_dwordx8 s[0:7], s[10:11], 0x0
	s_waitcnt lgkmcnt(0)
	v_writelane_b32 v254, s0, 32
	s_nop 1
	v_writelane_b32 v254, s1, 33
	v_writelane_b32 v254, s2, 34
	v_writelane_b32 v254, s3, 35
	v_writelane_b32 v254, s4, 36
	v_writelane_b32 v254, s5, 37
	v_writelane_b32 v254, s6, 38
	v_writelane_b32 v254, s7, 39
	s_add_u32 s6, s14, 0x8698000
	s_addc_u32 s7, s15, 0
	s_add_u32 s86, s14, 0x8600000
	s_addc_u32 s87, s15, 0
	s_add_u32 s46, s14, 0xceb8000
	s_addc_u32 s47, s15, 0
	s_cmpk_lg_i32 s16, 0x100
	s_cselect_b64 s[0:1], -1, 0
	v_writelane_b32 v254, s0, 40
	s_cmpk_lt_i32 s8, 0x100
	s_nop 0
	v_writelane_b32 v254, s1, 41
	s_cselect_b64 s[0:1], -1, 0
	v_writelane_b32 v254, s0, 42
	s_cmpk_lt_u32 s8, 0x100
	s_nop 0
	v_writelane_b32 v254, s1, 43
	s_cselect_b64 s[0:1], -1, 0
	v_writelane_b32 v254, s0, 44
	s_bfe_u32 s2, s8, 0x20003
	s_lshr_b32 s5, s8, 3
	v_writelane_b32 v254, s1, 45
	s_lshl_b32 s0, s8, 2
	s_and_b32 s1, s0, 28
	s_or_b32 s1, s2, s1
	s_lshl_b32 s1, s1, 8
	v_writelane_b32 v254, s1, 46
	s_and_b32 s0, s0, 0x380
	v_writelane_b32 v254, s0, 47
	s_addk_i32 s0, 0xff00
	v_writelane_b32 v254, s0, 48
	s_add_u32 s0, s14, 0xa6b8000
	s_addc_u32 s1, s15, 0
	v_writelane_b32 v254, s0, 49
	s_cmpk_lt_i32 s8, 0x2c0
	s_nop 0
	v_writelane_b32 v254, s1, 50
	s_cselect_b64 s[0:1], -1, 0
	v_writelane_b32 v254, s0, 51
	s_cmpk_lt_u32 s8, 0x2c0
	s_nop 0
	v_writelane_b32 v254, s1, 52
	s_cselect_b64 s[0:1], -1, 0
	v_writelane_b32 v254, s0, 53
	s_nop 1
	v_writelane_b32 v254, s1, 54
	s_add_u32 s0, s14, 0xfeb8000
	s_addc_u32 s1, s15, 0
	v_writelane_b32 v254, s0, 55
	s_nop 1
	v_writelane_b32 v254, s1, 56
	s_add_u32 s0, s14, 0xb6b8000
	s_addc_u32 s1, s15, 0
	v_writelane_b32 v254, s0, 57
	s_nop 1
	v_writelane_b32 v254, s1, 58
	s_add_u32 s0, s14, 0x16abb800
	v_writelane_b32 v254, s0, 59
	s_addc_u32 s0, s15, 0
	s_cmpk_gt_u32 s8, 0x7f
	v_writelane_b32 v254, s0, 60
	s_cselect_b64 s[0:1], -1, 0
	s_cmpk_eq_i32 s16, 0x100
	s_load_dwordx8 s[16:23], s[10:11], 0x80
	v_writelane_b32 v254, s0, 61
	s_mov_b64 s[10:11], 0x80
	s_nop 0
	v_writelane_b32 v254, s1, 62
	s_waitcnt lgkmcnt(0)
	v_writelane_b32 v254, s16, 63
	s_cselect_b64 s[0:1], -1, 0
	s_nop 0
	v_writelane_b32 v255, s17, 0
	v_writelane_b32 v255, s18, 1
	v_writelane_b32 v255, s19, 2
	v_writelane_b32 v255, s20, 3
	v_writelane_b32 v255, s21, 4
	v_writelane_b32 v255, s22, 5
	v_writelane_b32 v255, s23, 6
	v_writelane_b32 v255, s0, 7
	s_mov_b32 s16, s30
	s_nop 0
	v_writelane_b32 v255, s1, 8
	s_and_b64 s[0:1], s[0:1], exec
	s_cselect_b32 s0, 0x200, 0
	v_writelane_b32 v255, s0, 9
	s_lshl_b32 s0, s8, 4
	s_and_b32 s1, s0, 0x70
	s_and_b32 s3, s5, 0x1ffffff8
	s_add_i32 s3, s3, s1
	s_bfe_u32 s4, s8, 0x30003
	s_or_b32 s3, s3, s4
	s_addk_i32 s3, 0x180
	v_writelane_b32 v255, s3, 10
	s_add_i32 s1, s1, s5
	v_writelane_b32 v255, s5, 11
	s_add_i32 s3, s1, 0xf0
	v_writelane_b32 v255, s3, 12
	s_lshl_b32 s3, s8, 1
	s_lshr_b32 s5, s8, 6
	s_and_b32 s3, s3, 2
	s_add_i32 s3, s3, s5
	s_and_b32 s0, s0, 0x60
	s_lshl_b32 s3, s3, 3
	s_add_i32 s3, s3, s0
	s_addk_i32 s1, 0x70
	s_or_b32 s0, s3, s4
	s_cmpk_lt_u32 s8, 0x80
	s_cselect_b32 s0, s0, s1
	v_writelane_b32 v255, s0, 13
	s_add_u32 s0, s14, 0x15eb8000
	s_addc_u32 s1, s15, 0
	v_writelane_b32 v255, s0, 14
	s_movk_i32 s5, 0x1600
	s_movk_i32 s4, 0xbf
	v_writelane_b32 v255, s1, 15
	s_add_u32 s0, s14, 0x164b8000
	v_writelane_b32 v255, s0, 16
	s_addc_u32 s0, s15, 0
	s_cmpk_lt_i32 s8, 0x300
	v_writelane_b32 v255, s0, 17
	s_cselect_b64 s[0:1], -1, 0
	v_writelane_b32 v255, s0, 18
	s_cmpk_lt_u32 s8, 0x300
	s_movk_i32 s3, 0x17f
	v_writelane_b32 v255, s1, 19
	s_cselect_b64 s[0:1], -1, 0
	v_writelane_b32 v255, s0, 20
	s_ashr_i32 s71, s70, 31
	s_nop 0
	v_writelane_b32 v255, s1, 21
	s_lshl_b64 s[0:1], s[70:71], 10
	v_writelane_b32 v255, s0, 22
	s_nop 1
	v_writelane_b32 v255, s1, 23
	s_lshl_b64 s[0:1], s[70:71], 11
	v_writelane_b32 v255, s0, 24
	s_nop 1
	v_writelane_b32 v255, s1, 25
	s_add_u32 s0, s52, 0x2a000
	s_addc_u32 s1, s53, 0
	v_writelane_b32 v255, s0, 26
	s_mov_b64 s[52:53], 0x2000
	s_nop 0
	v_writelane_b32 v255, s1, 27
	s_add_u32 s0, s14, 0xa6b840c
	s_addc_u32 s1, s15, 0
	v_writelane_b32 v255, s0, 28
	s_nop 1
	v_writelane_b32 v255, s1, 29
	s_and_b32 s0, s8, 7
	s_lshl_b32 s0, s0, 10
	s_lshl_b32 s1, s2, 8
	s_or_b32 s0, s0, s1
	v_writelane_b32 v255, s0, 30
	v_writelane_b32 v255, s30, 31
	s_movk_i32 s1, 0xfff
	s_movk_i32 s2, 0x3bf
	v_writelane_b32 v255, s31, 32
	v_writelane_b32 v255, s68, 33
	v_writelane_b32 v255, s80, 34
	s_mov_b32 s0, 0x3e000000
	s_nop 0
	v_writelane_b32 v255, s81, 35
	v_writelane_b32 v255, s12, 36
	s_nop 1
	v_writelane_b32 v255, s13, 37
	v_writelane_b32 v255, s14, 38
	v_writelane_b32 v255, s15, 39
	v_mbcnt_lo_u32_b32 v6, -1, 0
	v_mbcnt_hi_u32_b32 v6, -1, v6
	v_lshlrev_b32_e32 v7, 2, v6
	v_readlane_b32 s88, v254, 63
	v_readlane_b32 s89, v255, 0
	v_readlane_b32 s90, v255, 1
	v_readlane_b32 s91, v255, 2
	v_readlane_b32 s92, v255, 3
	v_readlane_b32 s93, v255, 4
	v_readlane_b32 s94, v253, 1
	v_readlane_b32 s95, v253, 2
	s_nop 4
	s_load_dwordx4 s[36:39], s[94:95], 0x100
	global_load_dword v10, v7, s[62:63]
	global_load_dword v11, v7, s[88:89]
	global_load_dword v12, v7, s[90:91]
	global_load_dword v13, v7, s[92:93]
	global_load_dword v14, v7, s[62:63] offset:256
	global_load_dword v15, v7, s[88:89] offset:256
	global_load_dword v16, v7, s[90:91] offset:256
	global_load_dword v17, v7, s[92:93] offset:256
	global_load_dword v18, v7, s[62:63] offset:512
	global_load_dword v19, v7, s[88:89] offset:512
	global_load_dword v20, v7, s[90:91] offset:512
	global_load_dword v21, v7, s[92:93] offset:512
	global_load_dword v22, v7, s[62:63] offset:768
	global_load_dword v23, v7, s[88:89] offset:768
	global_load_dword v24, v7, s[90:91] offset:768
	global_load_dword v25, v7, s[92:93] offset:768
	s_waitcnt vmcnt(0) lgkmcnt(0)
	v_mul_f32_e32 v10, v10, v11
	v_mul_f32_e32 v12, v12, v13
	v_xor_b32_e32 v8, 0x80, v7
	ds_bpermute_b32 v9, v8, v10
	ds_bpermute_b32 v26, v8, v12
	s_waitcnt lgkmcnt(0)
	v_add_f32_e32 v10, v10, v9
	v_add_f32_e32 v12, v12, v26
	v_xor_b32_e32 v8, 0x40, v7
	ds_bpermute_b32 v9, v8, v10
	ds_bpermute_b32 v26, v8, v12
	s_waitcnt lgkmcnt(0)
	v_add_f32_e32 v10, v10, v9
	v_add_f32_e32 v12, v12, v26
	v_xor_b32_e32 v8, 0x20, v7
	ds_bpermute_b32 v9, v8, v10
	ds_bpermute_b32 v26, v8, v12
	s_waitcnt lgkmcnt(0)
	v_add_f32_e32 v10, v10, v9
	v_add_f32_e32 v12, v12, v26
	v_xor_b32_e32 v8, 0x10, v7
	ds_bpermute_b32 v9, v8, v10
	ds_bpermute_b32 v26, v8, v12
	s_waitcnt lgkmcnt(0)
	v_add_f32_e32 v10, v10, v9
	v_add_f32_e32 v12, v12, v26
	v_xor_b32_e32 v8, 0x8, v7
	ds_bpermute_b32 v9, v8, v10
	ds_bpermute_b32 v26, v8, v12
	s_waitcnt lgkmcnt(0)
	v_add_f32_e32 v10, v10, v9
	v_add_f32_e32 v12, v12, v26
	v_xor_b32_e32 v8, 0x4, v7
	ds_bpermute_b32 v9, v8, v10
	ds_bpermute_b32 v26, v8, v12
	s_waitcnt lgkmcnt(0)
	v_add_f32_e32 v10, v10, v9
	v_add_f32_e32 v12, v12, v26
	v_mul_f32_e32 v10, 0x3fb8aa3b, v10
	v_mul_f32_e32 v12, 0x3fb8aa3b, v12
	v_exp_f32_e32 v10, v10
	v_exp_f32_e32 v12, v12
	s_nop 1
	v_sub_f32_e32 v10, v10, v12
	v_add_f32_e32 v10, s36, v10
	s_nop 1
	v_readfirstlane_b32 s88, v10
	s_nop 1
	v_writelane_b32 v255, s88, 43
	v_mul_f32_e32 v14, v14, v15
	v_mul_f32_e32 v16, v16, v17
	v_xor_b32_e32 v8, 0x80, v7
	ds_bpermute_b32 v9, v8, v14
	ds_bpermute_b32 v26, v8, v16
	s_waitcnt lgkmcnt(0)
	v_add_f32_e32 v14, v14, v9
	v_add_f32_e32 v16, v16, v26
	v_xor_b32_e32 v8, 0x40, v7
	ds_bpermute_b32 v9, v8, v14
	ds_bpermute_b32 v26, v8, v16
	s_waitcnt lgkmcnt(0)
	v_add_f32_e32 v14, v14, v9
	v_add_f32_e32 v16, v16, v26
	v_xor_b32_e32 v8, 0x20, v7
	ds_bpermute_b32 v9, v8, v14
	ds_bpermute_b32 v26, v8, v16
	s_waitcnt lgkmcnt(0)
	v_add_f32_e32 v14, v14, v9
	v_add_f32_e32 v16, v16, v26
	v_xor_b32_e32 v8, 0x10, v7
	ds_bpermute_b32 v9, v8, v14
	ds_bpermute_b32 v26, v8, v16
	s_waitcnt lgkmcnt(0)
	v_add_f32_e32 v14, v14, v9
	v_add_f32_e32 v16, v16, v26
	v_xor_b32_e32 v8, 0x8, v7
	ds_bpermute_b32 v9, v8, v14
	ds_bpermute_b32 v26, v8, v16
	s_waitcnt lgkmcnt(0)
	v_add_f32_e32 v14, v14, v9
	v_add_f32_e32 v16, v16, v26
	v_xor_b32_e32 v8, 0x4, v7
	ds_bpermute_b32 v9, v8, v14
	ds_bpermute_b32 v26, v8, v16
	s_waitcnt lgkmcnt(0)
	v_add_f32_e32 v14, v14, v9
	v_add_f32_e32 v16, v16, v26
	v_mul_f32_e32 v14, 0x3fb8aa3b, v14
	v_mul_f32_e32 v16, 0x3fb8aa3b, v16
	v_exp_f32_e32 v14, v14
	v_exp_f32_e32 v16, v16
	s_nop 1
	v_sub_f32_e32 v14, v14, v16
	v_add_f32_e32 v14, s37, v14
	s_nop 1
	v_readfirstlane_b32 s88, v14
	s_nop 1
	v_writelane_b32 v255, s88, 44
	v_mul_f32_e32 v18, v18, v19
	v_mul_f32_e32 v20, v20, v21
	v_xor_b32_e32 v8, 0x80, v7
	ds_bpermute_b32 v9, v8, v18
	ds_bpermute_b32 v26, v8, v20
	s_waitcnt lgkmcnt(0)
	v_add_f32_e32 v18, v18, v9
	v_add_f32_e32 v20, v20, v26
	v_xor_b32_e32 v8, 0x40, v7
	ds_bpermute_b32 v9, v8, v18
	ds_bpermute_b32 v26, v8, v20
	s_waitcnt lgkmcnt(0)
	v_add_f32_e32 v18, v18, v9
	v_add_f32_e32 v20, v20, v26
	v_xor_b32_e32 v8, 0x20, v7
	ds_bpermute_b32 v9, v8, v18
	ds_bpermute_b32 v26, v8, v20
	s_waitcnt lgkmcnt(0)
	v_add_f32_e32 v18, v18, v9
	v_add_f32_e32 v20, v20, v26
	v_xor_b32_e32 v8, 0x10, v7
	ds_bpermute_b32 v9, v8, v18
	ds_bpermute_b32 v26, v8, v20
	s_waitcnt lgkmcnt(0)
	v_add_f32_e32 v18, v18, v9
	v_add_f32_e32 v20, v20, v26
	v_xor_b32_e32 v8, 0x8, v7
	ds_bpermute_b32 v9, v8, v18
	ds_bpermute_b32 v26, v8, v20
	s_waitcnt lgkmcnt(0)
	v_add_f32_e32 v18, v18, v9
	v_add_f32_e32 v20, v20, v26
	v_xor_b32_e32 v8, 0x4, v7
	ds_bpermute_b32 v9, v8, v18
	ds_bpermute_b32 v26, v8, v20
	s_waitcnt lgkmcnt(0)
	v_add_f32_e32 v18, v18, v9
	v_add_f32_e32 v20, v20, v26
	v_mul_f32_e32 v18, 0x3fb8aa3b, v18
	v_mul_f32_e32 v20, 0x3fb8aa3b, v20
	v_exp_f32_e32 v18, v18
	v_exp_f32_e32 v20, v20
	s_nop 1
	v_sub_f32_e32 v18, v18, v20
	v_add_f32_e32 v18, s38, v18
	s_nop 1
	v_readfirstlane_b32 s88, v18
	s_nop 1
	v_writelane_b32 v255, s88, 45
	v_mul_f32_e32 v22, v22, v23
	v_mul_f32_e32 v24, v24, v25
	v_xor_b32_e32 v8, 0x80, v7
	ds_bpermute_b32 v9, v8, v22
	ds_bpermute_b32 v26, v8, v24
	s_waitcnt lgkmcnt(0)
	v_add_f32_e32 v22, v22, v9
	v_add_f32_e32 v24, v24, v26
	v_xor_b32_e32 v8, 0x40, v7
	ds_bpermute_b32 v9, v8, v22
	ds_bpermute_b32 v26, v8, v24
	s_waitcnt lgkmcnt(0)
	v_add_f32_e32 v22, v22, v9
	v_add_f32_e32 v24, v24, v26
	v_xor_b32_e32 v8, 0x20, v7
	ds_bpermute_b32 v9, v8, v22
	ds_bpermute_b32 v26, v8, v24
	s_waitcnt lgkmcnt(0)
	v_add_f32_e32 v22, v22, v9
	v_add_f32_e32 v24, v24, v26
	v_xor_b32_e32 v8, 0x10, v7
	ds_bpermute_b32 v9, v8, v22
	ds_bpermute_b32 v26, v8, v24
	s_waitcnt lgkmcnt(0)
	v_add_f32_e32 v22, v22, v9
	v_add_f32_e32 v24, v24, v26
	v_xor_b32_e32 v8, 0x8, v7
	ds_bpermute_b32 v9, v8, v22
	ds_bpermute_b32 v26, v8, v24
	s_waitcnt lgkmcnt(0)
	v_add_f32_e32 v22, v22, v9
	v_add_f32_e32 v24, v24, v26
	v_xor_b32_e32 v8, 0x4, v7
	ds_bpermute_b32 v9, v8, v22
	ds_bpermute_b32 v26, v8, v24
	s_waitcnt lgkmcnt(0)
	v_add_f32_e32 v22, v22, v9
	v_add_f32_e32 v24, v24, v26
	v_mul_f32_e32 v22, 0x3fb8aa3b, v22
	v_mul_f32_e32 v24, 0x3fb8aa3b, v24
	v_exp_f32_e32 v22, v22
	v_exp_f32_e32 v24, v24
	s_nop 1
	v_sub_f32_e32 v22, v22, v24
	v_add_f32_e32 v22, s39, v22
	s_nop 1
	v_readfirstlane_b32 s88, v22
	s_nop 1
	v_writelane_b32 v255, s88, 46
	s_branch .LBB0_8

.LBB0_429:
	s_andn2_b64 vcc, exec, s[20:21]
	s_cbranch_vccnz .LBB0_478
	v_mov_b32_e32 v3, v202
	s_ashr_i32 s17, s16, 31
	v_and_b32_e32 v0, 63, v3
	s_lshl_b64 s[20:21], s[16:17], 2
	v_readlane_b32 s8, v254, 59
	s_add_u32 s90, s8, s20
	v_readlane_b32 s8, v254, 60
	s_addc_u32 s91, s8, s21
	v_cmp_lt_i32_e32 vcc, v209, v208
	s_ashr_i32 s19, s18, 31
	s_lshl_b64 s[20:21], s[18:19], 2
	v_cndmask_b32_e32 v9, v207, v209, vcc
	v_lshlrev_b32_e32 v166, 2, v9
	v_readlane_b32 s22, v253, 1
	v_readlane_b32 s23, v253, 2
	s_add_u32 s20, s22, s20
	s_addc_u32 s21, s23, s21
	s_load_dword s8, s[20:21], 0x100
	v_ashrrev_i32_e32 v2, 6, v3
	s_movk_i32 s20, 0x2200
	v_and_b32_e32 v168, 3, v2
	v_mul_lo_u32 v2, v2, s20
	v_and_b32_e32 v135, 31, v3
	v_bfe_u32 v5, v3, 5, 1
	s_movk_i32 s23, 0x90
	v_lshlrev_b32_e32 v134, 3, v5
	s_movk_i32 s20, 0x100
	v_cmp_gt_u32_e64 s[44:45], s20, v3
	s_lshl_b32 s20, s18, 7
	s_mul_i32 s22, s18, 0x1200000
	s_lshl_b32 s19, s18, 3
	s_ashr_i32 s21, s20, 31
	s_waitcnt lgkmcnt(0)
	v_sub_f32_e64 v167, 1.0, s8
	v_readlane_b32 s26, v255, 5
	v_readlane_b32 s27, v255, 6
	s_mov_b32 s17, 0
	s_mov_b32 s32, 0
	v_cmp_eq_u32_e64 s[40:41], 0, v3
	v_lshlrev_b32_e32 v170, 5, v168
	s_movk_i32 s88, 0x90
	v_mov_b32_e32 v139, v1
	s_movk_i32 s89, 0x600
	v_mov_b32_e32 v143, v1
	v_ashrrev_i32_e32 v10, 8, v3
	v_lshlrev_b32_e32 v171, 6, v10
	v_lshlrev_b32_e32 v172, 7, v10
	v_cmp_gt_u32_e32 vcc, 32, v0
	v_lshlrev_b32_e32 v0, 2, v0
	v_cmp_eq_u32_e64 s[42:43], 1, v10
	v_lshl_or_b32 v173, v168, 14, v0
	v_lshrrev_b32_e32 v13, 4, v3
	v_bfe_u32 v11, v3, 4, 2
	s_add_i32 s92, s18, 43
	s_nop 3
	v_readlane_b32 s93, v255, s92
	s_nop 1
	v_mov_b32_e32 v132, s93
	v_lshlrev_b32_e32 v4, 3, v3
	v_add_u32_e32 v6, 0x10000, v2
	v_and_b32_e32 v2, 56, v4
	v_and_b32_e32 v4, 0x78, v4
	v_mad_u32_u24 v9, v135, s23, v6
	v_lshl_or_b32 v8, v2, 1, v6
	v_mad_u32_u24 v10, v135, s83, v6
	v_lshl_or_b32 v0, v4, 1, v6
	v_bfe_u32 v6, v3, 3, 3
	v_mad_u32_u24 v175, v6, s23, v8
	v_or_b32_e32 v179, v10, v134
	v_or_b32_e32 v10, 12, v13
	s_movk_i32 s23, 0x600
	v_mad_u64_u32 v[136:137], s[24:25], v10, s83, v[0:1]
	v_mul_lo_u32 v138, v10, s23
	v_mov_b32_e32 v10, 0x7800
	v_mov_b32_e32 v12, 0x9000
	v_mad_u32_u24 v180, v11, s83, v0
	v_mul_u32_u24_e32 v8, 0x600, v11
	v_mad_u32_u24 v10, v11, s23, v10
	v_mad_u32_u24 v12, v11, s23, v12
	v_or_b32_e32 v11, 28, v13
	v_mad_u64_u32 v[140:141], s[24:25], v11, s83, v[0:1]
	v_readlane_b32 s24, v254, 30
	s_mul_hi_i32 s8, s18, 0x1200000
	v_readlane_b32 s25, v254, 31
	s_add_u32 s31, s24, s22
	s_addc_u32 s34, s25, s8
	s_add_u32 s22, s14, s22
	s_addc_u32 s8, s15, s8
	s_add_u32 s35, s22, 0x11fb8000
	s_addc_u32 s36, s8, 0
	s_lshl_b64 s[20:21], s[20:21], 2
	s_add_u32 s20, s26, s20
	v_ashrrev_i32_e32 v7, 3, v3
	v_mul_u32_u24_e32 v6, 0x600, v6
	s_addc_u32 s21, s27, s21
	v_lshlrev_b32_e32 v0, 4, v5
	s_movk_i32 s8, 0xffe0
	v_and_b32_e32 v169, 0xffffffe0, v7
	v_cndmask_b32_e64 v174, 0, 1.0, vcc
	v_add_u32_e32 v176, 0x480, v175
	v_add_u32_e32 v177, 0x900, v175
	v_add_u32_e32 v178, 0xd80, v175
	v_add_u32_e32 v181, 0x440, v180
	v_add_u32_e32 v182, 0x880, v180
	v_add_u32_e32 v137, 0x1100, v180
	v_add_u32_e32 v183, 0x1540, v180
	v_add_u32_e32 v184, 0x1980, v180
	v_mul_lo_u32 v142, v11, s23
	v_lshl_add_u64 v[144:145], s[20:21], 0, v[0:1]
	v_mov_b32_e32 v133, v132
	v_bfi_b32 v141, s8, v7, v3
	v_lshlrev_b32_e32 v146, 1, v2
	v_lshlrev_b32_e32 v148, 1, v6
	v_lshlrev_b32_e32 v150, 1, v4
	v_lshlrev_b32_e32 v152, 1, v8
	v_lshlrev_b32_e32 v154, 1, v10
	v_lshlrev_b32_e32 v156, 1, v12
	v_add_u32_e32 v185, v9, v134
	s_branch .LBB0_434
